# attn-C: one static s_setprio 1 for waves 4-7 during the attention phase (reset at phase end)
# baseline (speedup 1.0000x reference)
; __device__ __forceinline__ int bid_() { int b = (int)blockIdx.x; asm volatile("" : "+s"(b)); return b; }
; __device__ __forceinline__ void phase_attn_c(PP p, unsigned char* lds, int dry) {
;     ...
;     for (int u = bid_(); u < 1536; u += gridDim.x) {
;         int start, len, h, qb;
;         if (u < 1024) { const int sb = u >> 9; h = (u >> 6) & 7; qb = u & 63; start = TP + sb * 16384; len = 16384; }
;         else { const int v = u - 1024; const int sb = v >> 7; h = (v >> 4) & 7; qb = v & 15; start = sb * 4096; len = 4096; }
;         const size_t q0 = (size_t)(start + qb * 256);
;         att::attn_dense_body(QKV + q0 * 1536 + h * 128, QKV + (size_t)start * 1536 + 1024 + (h >> 2) * 128, QKV + (size_t)start * 1536 + 1280 + (h >> 2) * 128,
;                              O + q0 * 1024 + h * 128, len, (char*)lds, dry);
.LBB0_268:
	v_readfirstlane_b32 s4, v182
	s_nop 3
	s_lshr_b32 s4, s4, 6
	s_cmp_ge_u32 s4, 4
	s_cbranch_scc0 .Lmy_prio_done
	s_setprio 1

; __device__ __forceinline__ int bid_() { int b = (int)blockIdx.x; asm volatile("" : "+s"(b)); return b; }
; __device__ __forceinline__ void phase_attn_c(PP p, unsigned char* lds, int dry) {
;     ...
;     for (int u = bid_(); u < 1536; u += gridDim.x) {
;         int start, len, h, qb;
;         if (u < 1024) { const int sb = u >> 9; h = (u >> 6) & 7; qb = u & 63; start = TP + sb * 16384; len = 16384; }
;         else { const int v = u - 1024; const int sb = v >> 7; h = (v >> 4) & 7; qb = v & 15; start = sb * 4096; len = 4096; }
;         const size_t q0 = (size_t)(start + qb * 256);
;         att::attn_dense_body(QKV + q0 * 1536 + h * 128, QKV + (size_t)start * 1536 + 1024 + (h >> 2) * 128, QKV + (size_t)start * 1536 + 1280 + (h >> 2) * 128,
;                              O + q0 * 1024 + h * 128, len, (char*)lds, dry);
;         __syncthreads();
;     }
.LBB0_290:
	s_setprio 0
	s_mov_b32 s26, s46
	v_readlane_b32 s37, v254, 34
